# v27 + in-place tail for waves 0-3 (no accumulator copies)
# baseline (speedup 1.0000x reference)
.LBB0_1599:
	s_cmp_lt_u32 s68, s65
	s_cselect_b64 s[8:9], -1, 0
	v_cndmask_b32_e64 v0, 0, 1, s[8:9]
	s_add_i32 s3, s68, 2
	s_and_b32 s69, s3, 3
	s_lshl_b32 s69, s69, 15
	s_add_i32 s72, s68, 1
	s_and_b32 s72, s72, 3
	s_lshl_b32 s72, s72, 15
	s_and_b32 s71, s68, 3
	s_lshl_b32 s71, s71, 15
	s_mov_b64 s[4:5], -1
	s_cmp_ge_u32 s68, s59
	v_cmp_ne_u32_e64 s[8:9], 1, v0
	s_cbranch_scc1 .Lyka_xtail
	v_add_u32_e32 v0, s72, v208
	ds_read_b128 v[80:83], v0
	ds_read_b128 v[84:87], v0 offset:512
	ds_read_b128 v[6:9], v0 offset:2048
	ds_read_b128 v[112:115], v0 offset:2560
	ds_read_b128 v[10:13], v0 offset:4096
	ds_read_b128 v[116:119], v0 offset:4608
	ds_read_b128 v[2:5], v0 offset:6144
	ds_read_b128 v[120:123], v0 offset:6656
	s_and_b64 vcc, exec, s[8:9]
	s_cbranch_vccnz .LBB0_1608
	s_add_i32 s3, s69, s66
	s_mov_b32 s4, m0
	s_mov_b32 m0, s3
	s_nop 0
	global_load_lds_dwordx4 v[168:169], off
	s_mov_b32 m0, s4
	v_lshl_add_u64 v[14:15], v[168:169], 0, s[28:29]
	s_add_i32 s4, s3, 0x2000
	s_mov_b32 s5, m0
	s_mov_b32 m0, s4
	s_nop 0
	global_load_lds_dwordx4 v[14:15], off
	s_mov_b32 m0, s5
	v_lshl_add_u64 v[14:15], v[168:169], 0, s[40:41]
	s_add_i32 s4, s3, 0x4000
	s_mov_b32 s5, m0
	s_mov_b32 m0, s4
	s_nop 0
	global_load_lds_dwordx4 v[14:15], off
	s_mov_b32 m0, s5
	v_lshl_add_u64 v[14:15], v[168:169], 0, s[80:81]
	s_addk_i32 s3, 0x6000
	s_mov_b32 s4, m0
	s_mov_b32 m0, s3
	s_nop 0
	global_load_lds_dwordx4 v[14:15], off
	s_mov_b32 m0, s4

.Lyka_xtail:
	s_cmp_lg_u32 s59, s68
	s_cbranch_scc1 .LBB0_1610
	v_pk_add_f32 v[14:15], v[170:171], 0 op_sel_hi:[1,0]
	v_cvt_pk_bf16_f32 v124, v170, v172
	v_pk_add_f32 v[14:15], v[172:173], v[14:15]
	v_cvt_pk_bf16_f32 v125, v174, v176
	v_pk_add_f32 v[14:15], v[174:175], v[14:15]
	v_cvt_pk_bf16_f32 v126, v178, v180
	v_pk_add_f32 v[14:15], v[176:177], v[14:15]
	v_cvt_pk_bf16_f32 v127, v182, v184
	v_pk_add_f32 v[14:15], v[178:179], v[14:15]
	v_cvt_pk_bf16_f32 v128, v186, v188
	v_pk_add_f32 v[14:15], v[180:181], v[14:15]
	v_cvt_pk_bf16_f32 v129, v190, v192
	v_pk_add_f32 v[14:15], v[182:183], v[14:15]
	v_cvt_pk_bf16_f32 v130, v194, v196
	v_pk_add_f32 v[14:15], v[184:185], v[14:15]
	v_cvt_pk_bf16_f32 v131, v198, v200
	v_pk_add_f32 v[14:15], v[186:187], v[14:15]
	v_cvt_pk_bf16_f32 v132, v171, v173
	v_pk_add_f32 v[14:15], v[188:189], v[14:15]
	v_cvt_pk_bf16_f32 v133, v175, v177
	v_pk_add_f32 v[14:15], v[190:191], v[14:15]
	v_cvt_pk_bf16_f32 v134, v179, v181
	v_pk_add_f32 v[14:15], v[192:193], v[14:15]
	v_cvt_pk_bf16_f32 v135, v183, v185
	v_pk_add_f32 v[14:15], v[194:195], v[14:15]
	v_cvt_pk_bf16_f32 v136, v187, v189
	v_pk_add_f32 v[14:15], v[196:197], v[14:15]
	v_cvt_pk_bf16_f32 v137, v191, v193
	v_pk_add_f32 v[14:15], v[198:199], v[14:15]
	v_cvt_pk_bf16_f32 v138, v195, v197
	v_pk_add_f32 v[14:15], v[200:201], v[14:15]
	v_cvt_pk_bf16_f32 v139, v199, v201
	v_add_f32_e32 v0, v14, v15
	v_add_f32_e32 v210, v210, v0
	v_add_u32_e32 v14, s71, v209
	ds_read_b128 v[2:5], v14 offset:16384
	ds_read_b128 v[6:9], v14 offset:16896
	ds_read_b128 v[10:13], v14 offset:17408
	ds_read_b128 v[112:115], v14 offset:17920
	s_waitcnt lgkmcnt(0)
	v_mfma_f32_32x32x16_bf16 v[64:79], v[2:5], v[124:127], v[64:79]
	v_mfma_f32_32x32x16_bf16 v[48:63], v[6:9], v[124:127], v[48:63]
	v_mfma_f32_32x32x16_bf16 v[32:47], v[10:13], v[124:127], v[32:47]
	v_mfma_f32_32x32x16_bf16 v[16:31], v[112:115], v[124:127], v[16:31]
	ds_read_b128 v[2:5], v14 offset:20480
	ds_read_b128 v[6:9], v14 offset:20992
	ds_read_b128 v[10:13], v14 offset:21504
	ds_read_b128 v[112:115], v14 offset:22016
	s_waitcnt lgkmcnt(0)
	v_mfma_f32_32x32x16_bf16 v[64:79], v[2:5], v[128:131], v[64:79]
	v_mfma_f32_32x32x16_bf16 v[48:63], v[6:9], v[128:131], v[48:63]
	v_mfma_f32_32x32x16_bf16 v[32:47], v[10:13], v[128:131], v[32:47]
	v_mfma_f32_32x32x16_bf16 v[16:31], v[112:115], v[128:131], v[16:31]
	ds_read_b128 v[2:5], v14 offset:24576
	ds_read_b128 v[6:9], v14 offset:25088
	ds_read_b128 v[10:13], v14 offset:25600
	ds_read_b128 v[112:115], v14 offset:26112
	s_waitcnt lgkmcnt(0)
	v_mfma_f32_32x32x16_bf16 v[64:79], v[2:5], v[132:135], v[64:79]
	v_mfma_f32_32x32x16_bf16 v[48:63], v[6:9], v[132:135], v[48:63]
	v_mfma_f32_32x32x16_bf16 v[32:47], v[10:13], v[132:135], v[32:47]
	v_mfma_f32_32x32x16_bf16 v[16:31], v[112:115], v[132:135], v[16:31]
	ds_read_b128 v[2:5], v14 offset:28672
	ds_read_b128 v[6:9], v14 offset:29184
	ds_read_b128 v[10:13], v14 offset:29696
	ds_read_b128 v[112:115], v14 offset:30208
	s_waitcnt lgkmcnt(0)
	v_mfma_f32_32x32x16_bf16 v[64:79], v[2:5], v[136:139], v[64:79]
	v_mfma_f32_32x32x16_bf16 v[48:63], v[6:9], v[136:139], v[48:63]
	v_mfma_f32_32x32x16_bf16 v[32:47], v[10:13], v[136:139], v[32:47]
	v_mfma_f32_32x32x16_bf16 v[16:31], v[112:115], v[136:139], v[16:31]

.LBB0_2152:
	s_cmp_lt_u32 s78, s67
	s_cselect_b64 s[8:9], -1, 0
	v_cndmask_b32_e64 v0, 0, 1, s[8:9]
	s_add_i32 s3, s78, 2
	s_and_b32 s79, s3, 3
	s_lshl_b32 s79, s79, 15
	s_add_i32 s81, s78, 1
	s_and_b32 s81, s81, 3
	s_lshl_b32 s81, s81, 15
	s_and_b32 s80, s78, 3
	s_lshl_b32 s80, s80, 15
	s_mov_b64 s[4:5], -1
	s_cmp_ge_u32 s78, s66
	v_cmp_ne_u32_e64 s[8:9], 1, v0
	s_cbranch_scc1 .Lykb_xtail
	v_add_u32_e32 v0, s81, v208
	ds_read_b128 v[80:83], v0
	ds_read_b128 v[84:87], v0 offset:512
	ds_read_b128 v[6:9], v0 offset:2048
	ds_read_b128 v[112:115], v0 offset:2560
	ds_read_b128 v[10:13], v0 offset:4096
	ds_read_b128 v[116:119], v0 offset:4608
	ds_read_b128 v[2:5], v0 offset:6144
	ds_read_b128 v[120:123], v0 offset:6656
	s_and_b64 vcc, exec, s[8:9]
	s_cbranch_vccnz .LBB0_2161
	s_add_i32 s3, s79, s68
	s_mov_b32 s4, m0
	s_mov_b32 m0, s3
	s_nop 0
	global_load_lds_dwordx4 v[170:171], off
	s_mov_b32 m0, s4
	v_lshl_add_u64 v[14:15], v[170:171], 0, s[24:25]
	s_add_i32 s4, s3, 0x2000
	s_mov_b32 s5, m0
	s_mov_b32 m0, s4
	s_nop 0
	global_load_lds_dwordx4 v[14:15], off
	s_mov_b32 m0, s5
	v_lshl_add_u64 v[14:15], v[170:171], 0, s[26:27]
	s_add_i32 s4, s3, 0x4000
	s_mov_b32 s5, m0
	s_mov_b32 m0, s4
	s_nop 0
	global_load_lds_dwordx4 v[14:15], off
	s_mov_b32 m0, s5
	v_lshl_add_u64 v[14:15], v[170:171], 0, s[44:45]
	s_addk_i32 s3, 0x6000
	s_mov_b32 s4, m0
	s_mov_b32 m0, s3
	s_nop 0
	global_load_lds_dwordx4 v[14:15], off
	s_mov_b32 m0, s4

.Lykb_xtail:
	s_cmp_lg_u32 s66, s78
	s_cbranch_scc1 .LBB0_2163
	v_pk_add_f32 v[14:15], v[168:169], 0 op_sel_hi:[1,0]
	v_cvt_pk_bf16_f32 v124, v168, v172
	v_pk_add_f32 v[14:15], v[172:173], v[14:15]
	v_cvt_pk_bf16_f32 v125, v174, v176
	v_pk_add_f32 v[14:15], v[174:175], v[14:15]
	v_cvt_pk_bf16_f32 v126, v178, v180
	v_pk_add_f32 v[14:15], v[176:177], v[14:15]
	v_cvt_pk_bf16_f32 v127, v182, v184
	v_pk_add_f32 v[14:15], v[178:179], v[14:15]
	v_cvt_pk_bf16_f32 v128, v186, v188
	v_pk_add_f32 v[14:15], v[180:181], v[14:15]
	v_cvt_pk_bf16_f32 v129, v190, v192
	v_pk_add_f32 v[14:15], v[182:183], v[14:15]
	v_cvt_pk_bf16_f32 v130, v194, v196
	v_pk_add_f32 v[14:15], v[184:185], v[14:15]
	v_cvt_pk_bf16_f32 v131, v198, v200
	v_pk_add_f32 v[14:15], v[186:187], v[14:15]
	v_cvt_pk_bf16_f32 v132, v169, v173
	v_pk_add_f32 v[14:15], v[188:189], v[14:15]
	v_cvt_pk_bf16_f32 v133, v175, v177
	v_pk_add_f32 v[14:15], v[190:191], v[14:15]
	v_cvt_pk_bf16_f32 v134, v179, v181
	v_pk_add_f32 v[14:15], v[192:193], v[14:15]
	v_cvt_pk_bf16_f32 v135, v183, v185
	v_pk_add_f32 v[14:15], v[194:195], v[14:15]
	v_cvt_pk_bf16_f32 v136, v187, v189
	v_pk_add_f32 v[14:15], v[196:197], v[14:15]
	v_cvt_pk_bf16_f32 v137, v191, v193
	v_pk_add_f32 v[14:15], v[198:199], v[14:15]
	v_cvt_pk_bf16_f32 v138, v195, v197
	v_pk_add_f32 v[14:15], v[200:201], v[14:15]
	v_cvt_pk_bf16_f32 v139, v199, v201
	v_add_f32_e32 v0, v14, v15
	v_add_f32_e32 v210, v210, v0
	v_add_u32_e32 v14, s80, v209
	ds_read_b128 v[2:5], v14 offset:16384
	ds_read_b128 v[6:9], v14 offset:16896
	ds_read_b128 v[10:13], v14 offset:17408
	ds_read_b128 v[112:115], v14 offset:17920
	s_waitcnt lgkmcnt(0)
	v_mfma_f32_32x32x16_bf16 v[64:79], v[2:5], v[124:127], v[64:79]
	v_mfma_f32_32x32x16_bf16 v[48:63], v[6:9], v[124:127], v[48:63]
	v_mfma_f32_32x32x16_bf16 v[32:47], v[10:13], v[124:127], v[32:47]
	v_mfma_f32_32x32x16_bf16 v[16:31], v[112:115], v[124:127], v[16:31]
	ds_read_b128 v[2:5], v14 offset:20480
	ds_read_b128 v[6:9], v14 offset:20992
	ds_read_b128 v[10:13], v14 offset:21504
	ds_read_b128 v[112:115], v14 offset:22016
	s_waitcnt lgkmcnt(0)
	v_mfma_f32_32x32x16_bf16 v[64:79], v[2:5], v[128:131], v[64:79]
	v_mfma_f32_32x32x16_bf16 v[48:63], v[6:9], v[128:131], v[48:63]
	v_mfma_f32_32x32x16_bf16 v[32:47], v[10:13], v[128:131], v[32:47]
	v_mfma_f32_32x32x16_bf16 v[16:31], v[112:115], v[128:131], v[16:31]
	ds_read_b128 v[2:5], v14 offset:24576
	ds_read_b128 v[6:9], v14 offset:25088
	ds_read_b128 v[10:13], v14 offset:25600
	ds_read_b128 v[112:115], v14 offset:26112
	s_waitcnt lgkmcnt(0)
	v_mfma_f32_32x32x16_bf16 v[64:79], v[2:5], v[132:135], v[64:79]
	v_mfma_f32_32x32x16_bf16 v[48:63], v[6:9], v[132:135], v[48:63]
	v_mfma_f32_32x32x16_bf16 v[32:47], v[10:13], v[132:135], v[32:47]
	v_mfma_f32_32x32x16_bf16 v[16:31], v[112:115], v[132:135], v[16:31]
	ds_read_b128 v[2:5], v14 offset:28672
	ds_read_b128 v[6:9], v14 offset:29184
	ds_read_b128 v[10:13], v14 offset:29696
	ds_read_b128 v[112:115], v14 offset:30208
	s_waitcnt lgkmcnt(0)
	v_mfma_f32_32x32x16_bf16 v[64:79], v[2:5], v[136:139], v[64:79]
	v_mfma_f32_32x32x16_bf16 v[48:63], v[6:9], v[136:139], v[48:63]
	v_mfma_f32_32x32x16_bf16 v[32:47], v[10:13], v[136:139], v[32:47]
	v_mfma_f32_32x32x16_bf16 v[16:31], v[112:115], v[136:139], v[16:31]
